# k44 + strategy 2 (prologue de-serialisation): early vmcnt(0) after the Q loads removed in the layer-1 DA unit prologue so the tile-0 LDS-DMA issues under the Q-load latency
# speedup vs baseline: 1.0027x; 1.0027x over previous
; __device__ __forceinline__ int v_rd_base(int lane) { return ((lane & 3) << 3) | (((lane >> 2) & 3) << 6) | (((lane >> 4) & 1) << 5) | (((lane >> 5) & 1) << 8); }
; #define DPUB() do { asm volatile("s_waitcnt vmcnt(0)" ::: "memory"); __syncthreads(); } while (0)
; __device__ __forceinline__ void unit_body_da(const Unit& U, char* lds) {
;   int tid = threadIdx.x; asm volatile("" : "+v"(tid)); const int wid = __builtin_amdgcn_readfirstlane(tid >> 6), lane = tid & 63, r32 = lane & 31, hi = lane >> 5;
;   char* V_lds = lds; char* K_lds = lds + 2 * DA_VB;
;   float* ws = (float*)(lds + DA_WS_OFF) + wid * 64; float* li_l = ws; float* al_l = ws + 32;
;   float m_reg = -1e30f, l_reg = 0; f32x16 o[8] = {}; bf16x8 qr[8];
;   const bf16_t* Qw = U.Q + (long)(wid * QBLK + r32) * LDP + hi * 8;
; #pragma unroll
;   for (int d0 = 0; d0 < 8; ++d0) qr[d0] = ld8(Qw + d0 * 16);
;   const int vb0 = (int)(uintptr_t)V_lds + v_rd_base(lane);
;   const int ka0 = (int)(uintptr_t)K_lds + KSWZ(r32, hi * 16);
;   constexpr float C = SCALE * 1.4426950408889634f;
;   unsigned koff[2], voff[2][2];
; #pragma unroll
;   for (int i = 0; i < 2; ++i) { const int ob = (2 * wid + i) * 1024 + lane * 16;
;     { const int row = ob >> 8, cpos = (ob >> 4) & 15, c = cpos ^ (row & 7); koff[i] = (unsigned)(row * LDP + c * 8); }
;     { const int st = ob >> 9, kk = (st >> 2) * 8 + ((ob >> 6) & 7), c = (st & 3) * 32 + ((ob >> 1) & 31), k = (kk & ~0xC) | ((kk & 4) << 1) | ((kk & 8) >> 1);
;       voff[0][i] = (unsigned)(k * LDP + c); voff[1][i] = (unsigned)(k * LDP + 128 + c); } }
;   typedef __attribute__((address_space(3))) unsigned lds_u32;
;     ...
;   const int NT = U.nt;
;   DDMA(0, 0); DPUB();
.LBB0_1432:
	s_and_b64 vcc, exec, s[62:63]
	s_cbranch_vccz .LBB0_1404
	v_mov_b32_e32 v8, v210
	v_mov_b64_e32 v[2:3], s[56:57]
	v_readfirstlane_b32 s0, v8
	s_ashr_i32 s3, s0, 6
	s_and_b32 s0, s0, 0x3fffffc0
	s_lshl_b32 s0, s0, 2
	v_and_b32_e32 v234, 31, v8
	s_add_i32 s28, s0, 0
	s_lshl_b32 s60, s3, 5
	v_bfe_u32 v233, v8, 5, 1
	s_add_i32 s28, s28, 0x18000
	v_or_b32_e32 v0, s60, v234
	s_add_i32 s67, 0, 0x10000
	v_mad_i64_i32 v[2:3], s[0:1], v0, s92, v[2:3]
	v_lshlrev_b32_e32 v212, 4, v233
	v_mov_b32_e32 v213, v1
	s_cmp_lg_u32 s67, -1
	v_lshl_add_u64 v[2:3], v[2:3], 0, v[212:213]
	s_cselect_b32 s0, s67, 0
	s_lshl_b32 s29, s3, 11
	global_load_dwordx4 v[162:165], v[2:3], off
	global_load_dwordx4 v[166:169], v[2:3], off offset:32
	global_load_dwordx4 v[170:173], v[2:3], off offset:64
	global_load_dwordx4 v[174:177], v[2:3], off offset:96
	global_load_dwordx4 v[178:181], v[2:3], off offset:128
	global_load_dwordx4 v[182:185], v[2:3], off offset:160
	global_load_dwordx4 v[186:189], v[2:3], off offset:192
	global_load_dwordx4 v[190:193], v[2:3], off offset:224
	s_ashr_i32 s1, s29, 8
	v_lshrrev_b32_e32 v2, 1, v8
	v_and_b32_e32 v9, 63, v8
	v_bfe_u32 v0, v8, 2, 2
	s_and_b32 s3, s1, 0xfffff0
	v_and_b32_e32 v2, 8, v2
	v_lshlrev_b32_e32 v12, 4, v9
	s_lshr_b32 s1, s1, 1
	v_or3_b32 v0, v2, v0, s3
	v_and_or_b32 v0, s1, 4, v0
	v_or_b32_e32 v5, 0x400, v12
	v_mul_i32_i24_e32 v13, 0x1800, v0
	v_or_b32_e32 v0, s29, v12
	v_or_b32_e32 v4, s29, v5
	v_and_b32_e32 v3, 15, v8
	v_ashrrev_i32_e32 v0, 8, v0
	v_ashrrev_i32_e32 v4, 8, v4
	v_bitop3_b32 v2, v0, v3, 15 bitop3:0x6c
	v_bitop3_b32 v3, v4, v3, 15 bitop3:0x6c
	v_mul_i32_i24_e32 v4, 0x1800, v4
	v_lshlrev_b32_e32 v10, 3, v9
	v_mul_i32_i24_e32 v0, 0x1800, v0
	v_lshl_or_b32 v4, v3, 3, v4
	v_lshrrev_b32_e32 v3, 4, v5
	v_and_b32_e32 v11, 24, v10
	v_lshl_or_b32 v0, v2, 3, v0
	v_and_b32_e32 v14, 32, v8
	v_and_b32_e32 v3, 0x60, v3
	s_add_i32 s61, s67, s29
	v_or3_b32 v2, v11, v14, v13
	v_or3_b32 v6, v11, v3, v13
	v_lshl_add_u64 v[214:215], v[0:1], 1, s[24:25]
	s_mov_b32 m0, s61
	v_mov_b32_e32 v3, v1
	s_add_i32 s62, s29, 0
	global_load_lds_dwordx4 v[214:215], off
	v_lshl_add_u64 v[2:3], v[2:3], 1, s[22:23]
	s_mov_b32 m0, s62
	s_add_i32 s63, s62, 0x4000
	s_or_b32 s66, s29, 0x400
	global_load_lds_dwordx4 v[2:3], off
	v_lshl_add_u64 v[2:3], v[2:3], 0, s[8:9]
	s_mov_b32 m0, s63
	v_mov_b32_e32 v5, v1
	s_add_i32 s67, s67, s66
	global_load_lds_dwordx4 v[2:3], off
	v_lshl_add_u64 v[216:217], v[4:5], 1, s[24:25]
	s_mov_b32 m0, s67
	v_mov_b32_e32 v7, v1
	s_add_i32 s68, s62, 0x400
	global_load_lds_dwordx4 v[216:217], off
	v_lshl_add_u64 v[2:3], v[6:7], 1, s[22:23]
	s_mov_b32 m0, s68
	s_add_i32 s69, s62, 0x4400
	global_load_lds_dwordx4 v[2:3], off
	v_lshl_add_u64 v[2:3], v[2:3], 0, s[8:9]
	s_mov_b32 m0, s69
	v_lshlrev_b32_e32 v0, 1, v8
	global_load_lds_dwordx4 v[2:3], off
	v_and_b32_e32 v0, 32, v0
	v_and_or_b32 v0, v12, s93, v0
	v_and_b32_e32 v2, 0x100, v10
	s_cmp_lg_u32 0, -1
	v_or3_b32 v0, v0, v2, v11
	s_cselect_b32 s3, 0, 0
	v_add_u32_e32 v213, s3, v0
	s_add_i32 s3, s3, 0x8000
	v_add_u32_e32 v244, s3, v0
	v_or3_b32 v0, v13, v14, v11
	s_movk_i32 s3, 0x60
	v_bitop3_b32 v3, v233, v8, 15 bitop3:0x78
	v_lshl_add_u64 v[218:219], v[0:1], 1, s[22:23]
	v_bitop3_b32 v0, v9, s3, 64 bitop3:0xc8
	v_lshlrev_b32_e32 v2, 8, v234
	v_lshlrev_b32_e32 v3, 4, v3
	v_or3_b32 v0, v13, v0, v11
	v_mov_b32_e32 v14, v1
	v_mov_b32_e32 v15, v1
	v_add3_u32 v235, v2, s0, v3
	s_waitcnt vmcnt(0)
	v_cmp_gt_u32_e64 s[0:1], 32, v9
	v_lshl_add_u64 v[220:221], v[0:1], 1, s[22:23]
	v_mov_b32_e32 v0, v1
	v_mov_b32_e32 v2, v1
	v_mov_b32_e32 v3, v1
	v_mov_b32_e32 v4, v1
	v_mov_b32_e32 v6, v1
	v_mov_b32_e32 v8, v1
	v_mov_b32_e32 v9, v1
	v_mov_b32_e32 v10, v1
	v_mov_b32_e32 v11, v1
	v_mov_b32_e32 v12, v1
	v_mov_b32_e32 v13, v1
	v_mov_b64_e32 v[128:129], v[14:15]
	v_mov_b64_e32 v[112:113], v[14:15]
	v_mov_b64_e32 v[96:97], v[14:15]
	v_mov_b64_e32 v[80:81], v[14:15]
	v_mov_b64_e32 v[64:65], v[14:15]
	v_mov_b64_e32 v[48:49], v[14:15]
	v_mov_b64_e32 v[32:33], v[14:15]
	v_mov_b64_e32 v[126:127], v[12:13]
	v_mov_b64_e32 v[124:125], v[10:11]
	v_mov_b64_e32 v[122:123], v[8:9]
	v_mov_b64_e32 v[120:121], v[6:7]
	v_mov_b64_e32 v[118:119], v[4:5]
	v_mov_b64_e32 v[116:117], v[2:3]
	v_mov_b64_e32 v[114:115], v[0:1]
	v_mov_b64_e32 v[110:111], v[12:13]
	v_mov_b64_e32 v[108:109], v[10:11]
	v_mov_b64_e32 v[106:107], v[8:9]
	v_mov_b64_e32 v[104:105], v[6:7]
	v_mov_b64_e32 v[102:103], v[4:5]
	v_mov_b64_e32 v[100:101], v[2:3]
	v_mov_b64_e32 v[98:99], v[0:1]
	v_mov_b64_e32 v[94:95], v[12:13]
	v_mov_b64_e32 v[92:93], v[10:11]
	v_mov_b64_e32 v[90:91], v[8:9]
	v_mov_b64_e32 v[88:89], v[6:7]
	v_mov_b64_e32 v[86:87], v[4:5]
	v_mov_b64_e32 v[84:85], v[2:3]
	v_mov_b64_e32 v[82:83], v[0:1]
	v_mov_b64_e32 v[78:79], v[12:13]
	v_mov_b64_e32 v[76:77], v[10:11]
	v_mov_b64_e32 v[74:75], v[8:9]
	v_mov_b64_e32 v[72:73], v[6:7]
	v_mov_b64_e32 v[70:71], v[4:5]
	v_mov_b64_e32 v[68:69], v[2:3]
	v_mov_b64_e32 v[66:67], v[0:1]
	v_mov_b64_e32 v[62:63], v[12:13]
	v_mov_b64_e32 v[60:61], v[10:11]
	v_mov_b64_e32 v[58:59], v[8:9]
	v_mov_b64_e32 v[56:57], v[6:7]
	v_mov_b64_e32 v[54:55], v[4:5]
	v_mov_b64_e32 v[52:53], v[2:3]
	v_mov_b64_e32 v[50:51], v[0:1]
	v_mov_b64_e32 v[46:47], v[12:13]
	v_mov_b64_e32 v[44:45], v[10:11]
	v_mov_b64_e32 v[42:43], v[8:9]
	v_mov_b64_e32 v[40:41], v[6:7]
	v_mov_b64_e32 v[38:39], v[4:5]
	v_mov_b64_e32 v[36:37], v[2:3]
	v_mov_b64_e32 v[34:35], v[0:1]
	v_mov_b64_e32 v[30:31], v[12:13]
	v_mov_b64_e32 v[28:29], v[10:11]
	v_mov_b64_e32 v[26:27], v[8:9]
	v_mov_b64_e32 v[24:25], v[6:7]
	v_mov_b64_e32 v[22:23], v[4:5]
	v_mov_b64_e32 v[20:21], v[2:3]
	v_mov_b64_e32 v[18:19], v[0:1]
	v_mov_b64_e32 v[16:17], v[14:15]
	s_mov_b32 s80, 2
	v_xor_b32_e32 v236, 32, v235
	v_xor_b32_e32 v238, 64, v235
	v_xor_b32_e32 v239, 0x60, v235
	v_xor_b32_e32 v240, 0x80, v235
	v_xor_b32_e32 v241, 0xa0, v235
	v_xor_b32_e32 v242, 0xc0, v235
	v_xor_b32_e32 v243, 0xe0, v235
	v_lshl_add_u32 v237, v234, 2, s28
	v_mov_b32_e32 v245, 0
	v_mov_b32_e32 v246, 0xf149f2ca
	s_mov_b64 s[22:23], 0
	v_mov_b64_e32 v[14:15], v[12:13]
	v_mov_b64_e32 v[12:13], v[10:11]
	v_mov_b64_e32 v[10:11], v[8:9]
	v_mov_b64_e32 v[8:9], v[6:7]
	v_mov_b64_e32 v[6:7], v[4:5]
	v_mov_b64_e32 v[4:5], v[2:3]
	v_mov_b64_e32 v[2:3], v[0:1]
	s_waitcnt vmcnt(0) lgkmcnt(0)
	s_barrier
	s_cmp_lt_u32 s29, 0x2000
	s_cbranch_scc1 .Lda_l1_lead_in
	s_barrier
